# FFN1 SwiGLU epilogue hand-rewritten with packed f32 ops (same math, all f32, half the VALU instructions)
# speedup vs baseline: 1.0065x; 1.0065x over previous
.LBB0_1498:
	v_mov_b32_e32 v142, v147
	v_mov_b32_e32 v153, v146
	s_lshl_b32 s0, s63, 8
	s_add_i32 s0, s0, s53
	v_add_u32_e32 v142, s0, v142
	v_ashrrev_i32_e32 v143, 31, v142
	v_lshl_add_u64 v[144:145], v[142:143], 2, s[18:19]
	global_load_dword v152, v[144:145], off
	global_load_dword v233, v[144:145], off offset:64
	global_load_dword v234, v[144:145], off offset:128
	global_load_dword v235, v[144:145], off offset:192
	global_load_dword v236, v[144:145], off offset:512
	global_load_dword v237, v[144:145], off offset:576
	global_load_dword v238, v[144:145], off offset:640
	global_load_dword v239, v[144:145], off offset:704
	s_lshl_b32 s0, s62, 7
	s_or_b32 s0, s0, s54
	v_lshl_add_u32 v156, v153, 3, s0
	v_ashrrev_i32_e32 v157, 31, v156
	v_mov_b64_e32 v[162:163], s[10:11]
	v_mad_i64_i32 v[160:161], s[0:1], v142, s59, v[162:163]
	v_lshlrev_b64 v[162:163], 1, v[156:157]
	v_lshl_add_u64 v[160:161], v[160:161], 0, v[162:163]
	v_mov_b32_e32 v164, 1.0
	v_mov_b32_e32 v165, 1.0
	s_waitcnt vmcnt(0)
	v_mul_f32_e32 v166, 0xbfb8aa3b, v152
	v_mul_f32_e32 v168, v152, v152
	v_pk_mul_f32 v[170:171], v[120:121], v[166:167] op_sel_hi:[1,0]
	v_pk_mul_f32 v[172:173], v[122:123], v[166:167] op_sel_hi:[1,0]
	v_pk_mul_f32 v[174:175], v[112:113], v[166:167] op_sel_hi:[1,0]
	v_pk_mul_f32 v[176:177], v[114:115], v[166:167] op_sel_hi:[1,0]
	v_pk_mul_f32 v[178:179], v[120:121], v[124:125]
	v_pk_mul_f32 v[180:181], v[122:123], v[126:127]
	v_pk_mul_f32 v[182:183], v[112:113], v[116:117]
	v_pk_mul_f32 v[184:185], v[114:115], v[118:119]
	v_exp_f32_e32 v170, v170
	v_exp_f32_e32 v171, v171
	v_exp_f32_e32 v172, v172
	v_exp_f32_e32 v173, v173
	v_exp_f32_e32 v174, v174
	v_exp_f32_e32 v175, v175
	v_exp_f32_e32 v176, v176
	v_exp_f32_e32 v177, v177
	s_nop 0
	v_pk_add_f32 v[170:171], v[170:171], v[164:165]
	v_pk_add_f32 v[172:173], v[172:173], v[164:165]
	v_pk_add_f32 v[174:175], v[174:175], v[164:165]
	v_pk_add_f32 v[176:177], v[176:177], v[164:165]
	v_rcp_f32_e32 v170, v170
	v_rcp_f32_e32 v171, v171
	v_rcp_f32_e32 v172, v172
	v_rcp_f32_e32 v173, v173
	v_rcp_f32_e32 v174, v174
	v_rcp_f32_e32 v175, v175
	v_rcp_f32_e32 v176, v176
	v_rcp_f32_e32 v177, v177
	s_nop 0
	v_pk_mul_f32 v[170:171], v[170:171], v[168:169] op_sel_hi:[1,0]
	v_pk_mul_f32 v[172:173], v[172:173], v[168:169] op_sel_hi:[1,0]
	v_pk_mul_f32 v[174:175], v[174:175], v[168:169] op_sel_hi:[1,0]
	v_pk_mul_f32 v[176:177], v[176:177], v[168:169] op_sel_hi:[1,0]
	v_pk_mul_f32 v[178:179], v[178:179], v[170:171]
	v_pk_mul_f32 v[180:181], v[180:181], v[172:173]
	v_pk_mul_f32 v[182:183], v[182:183], v[174:175]
	v_pk_mul_f32 v[184:185], v[184:185], v[176:177]
	v_cvt_pk_bf16_f32 v186, v178, v179
	v_cvt_pk_bf16_f32 v187, v180, v181
	v_cvt_pk_bf16_f32 v188, v182, v183
	v_cvt_pk_bf16_f32 v189, v184, v185
	global_store_dwordx4 v[160:161], v[186:189], off
	s_nop 1
	s_mov_b64 s[98:99], 0x2c000
	v_lshl_add_u64 v[160:161], v[160:161], 0, s[98:99]
	v_mul_f32_e32 v166, 0xbfb8aa3b, v233
	v_mul_f32_e32 v168, v233, v233
	v_pk_mul_f32 v[170:171], v[104:105], v[166:167] op_sel_hi:[1,0]
	v_pk_mul_f32 v[172:173], v[106:107], v[166:167] op_sel_hi:[1,0]
	v_pk_mul_f32 v[174:175], v[96:97], v[166:167] op_sel_hi:[1,0]
	v_pk_mul_f32 v[176:177], v[98:99], v[166:167] op_sel_hi:[1,0]
	v_pk_mul_f32 v[178:179], v[104:105], v[108:109]
	v_pk_mul_f32 v[180:181], v[106:107], v[110:111]
	v_pk_mul_f32 v[182:183], v[96:97], v[100:101]
	v_pk_mul_f32 v[184:185], v[98:99], v[102:103]
	v_exp_f32_e32 v170, v170
	v_exp_f32_e32 v171, v171
	v_exp_f32_e32 v172, v172
	v_exp_f32_e32 v173, v173
	v_exp_f32_e32 v174, v174
	v_exp_f32_e32 v175, v175
	v_exp_f32_e32 v176, v176
	v_exp_f32_e32 v177, v177
	s_nop 0
	v_pk_add_f32 v[170:171], v[170:171], v[164:165]
	v_pk_add_f32 v[172:173], v[172:173], v[164:165]
	v_pk_add_f32 v[174:175], v[174:175], v[164:165]
	v_pk_add_f32 v[176:177], v[176:177], v[164:165]
	v_rcp_f32_e32 v170, v170
	v_rcp_f32_e32 v171, v171
	v_rcp_f32_e32 v172, v172
	v_rcp_f32_e32 v173, v173
	v_rcp_f32_e32 v174, v174
	v_rcp_f32_e32 v175, v175
	v_rcp_f32_e32 v176, v176
	v_rcp_f32_e32 v177, v177
	s_nop 0
	v_pk_mul_f32 v[170:171], v[170:171], v[168:169] op_sel_hi:[1,0]
	v_pk_mul_f32 v[172:173], v[172:173], v[168:169] op_sel_hi:[1,0]
	v_pk_mul_f32 v[174:175], v[174:175], v[168:169] op_sel_hi:[1,0]
	v_pk_mul_f32 v[176:177], v[176:177], v[168:169] op_sel_hi:[1,0]
	v_pk_mul_f32 v[178:179], v[178:179], v[170:171]
	v_pk_mul_f32 v[180:181], v[180:181], v[172:173]
	v_pk_mul_f32 v[182:183], v[182:183], v[174:175]
	v_pk_mul_f32 v[184:185], v[184:185], v[176:177]
	v_cvt_pk_bf16_f32 v186, v178, v179
	v_cvt_pk_bf16_f32 v187, v180, v181
	v_cvt_pk_bf16_f32 v188, v182, v183
	v_cvt_pk_bf16_f32 v189, v184, v185
	global_store_dwordx4 v[160:161], v[186:189], off
	s_nop 1
	s_mov_b64 s[98:99], 0x2c000
	v_lshl_add_u64 v[160:161], v[160:161], 0, s[98:99]
	v_mul_f32_e32 v166, 0xbfb8aa3b, v234
	v_mul_f32_e32 v168, v234, v234
	v_pk_mul_f32 v[170:171], v[88:89], v[166:167] op_sel_hi:[1,0]
	v_pk_mul_f32 v[172:173], v[90:91], v[166:167] op_sel_hi:[1,0]
	v_pk_mul_f32 v[174:175], v[80:81], v[166:167] op_sel_hi:[1,0]
	v_pk_mul_f32 v[176:177], v[82:83], v[166:167] op_sel_hi:[1,0]
	v_pk_mul_f32 v[178:179], v[88:89], v[92:93]
	v_pk_mul_f32 v[180:181], v[90:91], v[94:95]
	v_pk_mul_f32 v[182:183], v[80:81], v[84:85]
	v_pk_mul_f32 v[184:185], v[82:83], v[86:87]
	v_exp_f32_e32 v170, v170
	v_exp_f32_e32 v171, v171
	v_exp_f32_e32 v172, v172
	v_exp_f32_e32 v173, v173
	v_exp_f32_e32 v174, v174
	v_exp_f32_e32 v175, v175
	v_exp_f32_e32 v176, v176
	v_exp_f32_e32 v177, v177
	s_nop 0
	v_pk_add_f32 v[170:171], v[170:171], v[164:165]
	v_pk_add_f32 v[172:173], v[172:173], v[164:165]
	v_pk_add_f32 v[174:175], v[174:175], v[164:165]
	v_pk_add_f32 v[176:177], v[176:177], v[164:165]
	v_rcp_f32_e32 v170, v170
	v_rcp_f32_e32 v171, v171
	v_rcp_f32_e32 v172, v172
	v_rcp_f32_e32 v173, v173
	v_rcp_f32_e32 v174, v174
	v_rcp_f32_e32 v175, v175
	v_rcp_f32_e32 v176, v176
	v_rcp_f32_e32 v177, v177
	s_nop 0
	v_pk_mul_f32 v[170:171], v[170:171], v[168:169] op_sel_hi:[1,0]
	v_pk_mul_f32 v[172:173], v[172:173], v[168:169] op_sel_hi:[1,0]
	v_pk_mul_f32 v[174:175], v[174:175], v[168:169] op_sel_hi:[1,0]
	v_pk_mul_f32 v[176:177], v[176:177], v[168:169] op_sel_hi:[1,0]
	v_pk_mul_f32 v[178:179], v[178:179], v[170:171]
	v_pk_mul_f32 v[180:181], v[180:181], v[172:173]
	v_pk_mul_f32 v[182:183], v[182:183], v[174:175]
	v_pk_mul_f32 v[184:185], v[184:185], v[176:177]
	v_cvt_pk_bf16_f32 v186, v178, v179
	v_cvt_pk_bf16_f32 v187, v180, v181
	v_cvt_pk_bf16_f32 v188, v182, v183
	v_cvt_pk_bf16_f32 v189, v184, v185
	global_store_dwordx4 v[160:161], v[186:189], off
	s_nop 1
	s_mov_b64 s[98:99], 0x2c000
	v_lshl_add_u64 v[160:161], v[160:161], 0, s[98:99]
	v_mul_f32_e32 v166, 0xbfb8aa3b, v235
	v_mul_f32_e32 v168, v235, v235
	v_pk_mul_f32 v[170:171], v[72:73], v[166:167] op_sel_hi:[1,0]
	v_pk_mul_f32 v[172:173], v[74:75], v[166:167] op_sel_hi:[1,0]
	v_pk_mul_f32 v[174:175], v[64:65], v[166:167] op_sel_hi:[1,0]
	v_pk_mul_f32 v[176:177], v[66:67], v[166:167] op_sel_hi:[1,0]
	v_pk_mul_f32 v[178:179], v[72:73], v[76:77]
	v_pk_mul_f32 v[180:181], v[74:75], v[78:79]
	v_pk_mul_f32 v[182:183], v[64:65], v[68:69]
	v_pk_mul_f32 v[184:185], v[66:67], v[70:71]
	v_exp_f32_e32 v170, v170
	v_exp_f32_e32 v171, v171
	v_exp_f32_e32 v172, v172
	v_exp_f32_e32 v173, v173
	v_exp_f32_e32 v174, v174
	v_exp_f32_e32 v175, v175
	v_exp_f32_e32 v176, v176
	v_exp_f32_e32 v177, v177
	s_nop 0
	v_pk_add_f32 v[170:171], v[170:171], v[164:165]
	v_pk_add_f32 v[172:173], v[172:173], v[164:165]
	v_pk_add_f32 v[174:175], v[174:175], v[164:165]
	v_pk_add_f32 v[176:177], v[176:177], v[164:165]
	v_rcp_f32_e32 v170, v170
	v_rcp_f32_e32 v171, v171
	v_rcp_f32_e32 v172, v172
	v_rcp_f32_e32 v173, v173
	v_rcp_f32_e32 v174, v174
	v_rcp_f32_e32 v175, v175
	v_rcp_f32_e32 v176, v176
	v_rcp_f32_e32 v177, v177
	s_nop 0
	v_pk_mul_f32 v[170:171], v[170:171], v[168:169] op_sel_hi:[1,0]
	v_pk_mul_f32 v[172:173], v[172:173], v[168:169] op_sel_hi:[1,0]
	v_pk_mul_f32 v[174:175], v[174:175], v[168:169] op_sel_hi:[1,0]
	v_pk_mul_f32 v[176:177], v[176:177], v[168:169] op_sel_hi:[1,0]
	v_pk_mul_f32 v[178:179], v[178:179], v[170:171]
	v_pk_mul_f32 v[180:181], v[180:181], v[172:173]
	v_pk_mul_f32 v[182:183], v[182:183], v[174:175]
	v_pk_mul_f32 v[184:185], v[184:185], v[176:177]
	v_cvt_pk_bf16_f32 v186, v178, v179
	v_cvt_pk_bf16_f32 v187, v180, v181
	v_cvt_pk_bf16_f32 v188, v182, v183
	v_cvt_pk_bf16_f32 v189, v184, v185
	global_store_dwordx4 v[160:161], v[186:189], off
	s_nop 1
	s_mov_b64 s[98:99], 0xdc000
	v_lshl_add_u64 v[160:161], v[160:161], 0, s[98:99]
	v_mul_f32_e32 v166, 0xbfb8aa3b, v236
	v_mul_f32_e32 v168, v236, v236
	v_pk_mul_f32 v[170:171], v[56:57], v[166:167] op_sel_hi:[1,0]
	v_pk_mul_f32 v[172:173], v[58:59], v[166:167] op_sel_hi:[1,0]
	v_pk_mul_f32 v[174:175], v[48:49], v[166:167] op_sel_hi:[1,0]
	v_pk_mul_f32 v[176:177], v[50:51], v[166:167] op_sel_hi:[1,0]
	v_pk_mul_f32 v[178:179], v[56:57], v[60:61]
	v_pk_mul_f32 v[180:181], v[58:59], v[62:63]
	v_pk_mul_f32 v[182:183], v[48:49], v[52:53]
	v_pk_mul_f32 v[184:185], v[50:51], v[54:55]
	v_exp_f32_e32 v170, v170
	v_exp_f32_e32 v171, v171
	v_exp_f32_e32 v172, v172
	v_exp_f32_e32 v173, v173
	v_exp_f32_e32 v174, v174
	v_exp_f32_e32 v175, v175
	v_exp_f32_e32 v176, v176
	v_exp_f32_e32 v177, v177
	s_nop 0
	v_pk_add_f32 v[170:171], v[170:171], v[164:165]
	v_pk_add_f32 v[172:173], v[172:173], v[164:165]
	v_pk_add_f32 v[174:175], v[174:175], v[164:165]
	v_pk_add_f32 v[176:177], v[176:177], v[164:165]
	v_rcp_f32_e32 v170, v170
	v_rcp_f32_e32 v171, v171
	v_rcp_f32_e32 v172, v172
	v_rcp_f32_e32 v173, v173
	v_rcp_f32_e32 v174, v174
	v_rcp_f32_e32 v175, v175
	v_rcp_f32_e32 v176, v176
	v_rcp_f32_e32 v177, v177
	s_nop 0
	v_pk_mul_f32 v[170:171], v[170:171], v[168:169] op_sel_hi:[1,0]
	v_pk_mul_f32 v[172:173], v[172:173], v[168:169] op_sel_hi:[1,0]
	v_pk_mul_f32 v[174:175], v[174:175], v[168:169] op_sel_hi:[1,0]
	v_pk_mul_f32 v[176:177], v[176:177], v[168:169] op_sel_hi:[1,0]
	v_pk_mul_f32 v[178:179], v[178:179], v[170:171]
	v_pk_mul_f32 v[180:181], v[180:181], v[172:173]
	v_pk_mul_f32 v[182:183], v[182:183], v[174:175]
	v_pk_mul_f32 v[184:185], v[184:185], v[176:177]
	v_cvt_pk_bf16_f32 v186, v178, v179
	v_cvt_pk_bf16_f32 v187, v180, v181
	v_cvt_pk_bf16_f32 v188, v182, v183
	v_cvt_pk_bf16_f32 v189, v184, v185
	global_store_dwordx4 v[160:161], v[186:189], off
	s_nop 1
	s_mov_b64 s[98:99], 0x2c000
	v_lshl_add_u64 v[160:161], v[160:161], 0, s[98:99]
	v_mul_f32_e32 v166, 0xbfb8aa3b, v237
	v_mul_f32_e32 v168, v237, v237
	v_pk_mul_f32 v[170:171], v[40:41], v[166:167] op_sel_hi:[1,0]
	v_pk_mul_f32 v[172:173], v[42:43], v[166:167] op_sel_hi:[1,0]
	v_pk_mul_f32 v[174:175], v[32:33], v[166:167] op_sel_hi:[1,0]
	v_pk_mul_f32 v[176:177], v[34:35], v[166:167] op_sel_hi:[1,0]
	v_pk_mul_f32 v[178:179], v[40:41], v[44:45]
	v_pk_mul_f32 v[180:181], v[42:43], v[46:47]
	v_pk_mul_f32 v[182:183], v[32:33], v[36:37]
	v_pk_mul_f32 v[184:185], v[34:35], v[38:39]
	v_exp_f32_e32 v170, v170
	v_exp_f32_e32 v171, v171
	v_exp_f32_e32 v172, v172
	v_exp_f32_e32 v173, v173
	v_exp_f32_e32 v174, v174
	v_exp_f32_e32 v175, v175
	v_exp_f32_e32 v176, v176
	v_exp_f32_e32 v177, v177
	s_nop 0
	v_pk_add_f32 v[170:171], v[170:171], v[164:165]
	v_pk_add_f32 v[172:173], v[172:173], v[164:165]
	v_pk_add_f32 v[174:175], v[174:175], v[164:165]
	v_pk_add_f32 v[176:177], v[176:177], v[164:165]
	v_rcp_f32_e32 v170, v170
	v_rcp_f32_e32 v171, v171
	v_rcp_f32_e32 v172, v172
	v_rcp_f32_e32 v173, v173
	v_rcp_f32_e32 v174, v174
	v_rcp_f32_e32 v175, v175
	v_rcp_f32_e32 v176, v176
	v_rcp_f32_e32 v177, v177
	s_nop 0
	v_pk_mul_f32 v[170:171], v[170:171], v[168:169] op_sel_hi:[1,0]
	v_pk_mul_f32 v[172:173], v[172:173], v[168:169] op_sel_hi:[1,0]
	v_pk_mul_f32 v[174:175], v[174:175], v[168:169] op_sel_hi:[1,0]
	v_pk_mul_f32 v[176:177], v[176:177], v[168:169] op_sel_hi:[1,0]
	v_pk_mul_f32 v[178:179], v[178:179], v[170:171]
	v_pk_mul_f32 v[180:181], v[180:181], v[172:173]
	v_pk_mul_f32 v[182:183], v[182:183], v[174:175]
	v_pk_mul_f32 v[184:185], v[184:185], v[176:177]
	v_cvt_pk_bf16_f32 v186, v178, v179
	v_cvt_pk_bf16_f32 v187, v180, v181
	v_cvt_pk_bf16_f32 v188, v182, v183
	v_cvt_pk_bf16_f32 v189, v184, v185
	global_store_dwordx4 v[160:161], v[186:189], off
	s_nop 1
	s_mov_b64 s[98:99], 0x2c000
	v_lshl_add_u64 v[160:161], v[160:161], 0, s[98:99]
	v_mul_f32_e32 v166, 0xbfb8aa3b, v238
	v_mul_f32_e32 v168, v238, v238
	v_pk_mul_f32 v[170:171], v[24:25], v[166:167] op_sel_hi:[1,0]
	v_pk_mul_f32 v[172:173], v[26:27], v[166:167] op_sel_hi:[1,0]
	v_pk_mul_f32 v[174:175], v[16:17], v[166:167] op_sel_hi:[1,0]
	v_pk_mul_f32 v[176:177], v[18:19], v[166:167] op_sel_hi:[1,0]
	v_pk_mul_f32 v[178:179], v[24:25], v[28:29]
	v_pk_mul_f32 v[180:181], v[26:27], v[30:31]
	v_pk_mul_f32 v[182:183], v[16:17], v[20:21]
	v_pk_mul_f32 v[184:185], v[18:19], v[22:23]
	v_exp_f32_e32 v170, v170
	v_exp_f32_e32 v171, v171
	v_exp_f32_e32 v172, v172
	v_exp_f32_e32 v173, v173
	v_exp_f32_e32 v174, v174
	v_exp_f32_e32 v175, v175
	v_exp_f32_e32 v176, v176
	v_exp_f32_e32 v177, v177
	s_nop 0
	v_pk_add_f32 v[170:171], v[170:171], v[164:165]
	v_pk_add_f32 v[172:173], v[172:173], v[164:165]
	v_pk_add_f32 v[174:175], v[174:175], v[164:165]
	v_pk_add_f32 v[176:177], v[176:177], v[164:165]
	v_rcp_f32_e32 v170, v170
	v_rcp_f32_e32 v171, v171
	v_rcp_f32_e32 v172, v172
	v_rcp_f32_e32 v173, v173
	v_rcp_f32_e32 v174, v174
	v_rcp_f32_e32 v175, v175
	v_rcp_f32_e32 v176, v176
	v_rcp_f32_e32 v177, v177
	s_nop 0
	v_pk_mul_f32 v[170:171], v[170:171], v[168:169] op_sel_hi:[1,0]
	v_pk_mul_f32 v[172:173], v[172:173], v[168:169] op_sel_hi:[1,0]
	v_pk_mul_f32 v[174:175], v[174:175], v[168:169] op_sel_hi:[1,0]
	v_pk_mul_f32 v[176:177], v[176:177], v[168:169] op_sel_hi:[1,0]
	v_pk_mul_f32 v[178:179], v[178:179], v[170:171]
	v_pk_mul_f32 v[180:181], v[180:181], v[172:173]
	v_pk_mul_f32 v[182:183], v[182:183], v[174:175]
	v_pk_mul_f32 v[184:185], v[184:185], v[176:177]
	v_cvt_pk_bf16_f32 v186, v178, v179
	v_cvt_pk_bf16_f32 v187, v180, v181
	v_cvt_pk_bf16_f32 v188, v182, v183
	v_cvt_pk_bf16_f32 v189, v184, v185
	global_store_dwordx4 v[160:161], v[186:189], off
	s_nop 1
	s_mov_b64 s[98:99], 0x2c000
	v_lshl_add_u64 v[160:161], v[160:161], 0, s[98:99]
	v_mul_f32_e32 v166, 0xbfb8aa3b, v239
	v_mul_f32_e32 v168, v239, v239
	v_pk_mul_f32 v[170:171], v[8:9], v[166:167] op_sel_hi:[1,0]
	v_pk_mul_f32 v[172:173], v[10:11], v[166:167] op_sel_hi:[1,0]
	v_pk_mul_f32 v[174:175], v[4:5], v[166:167] op_sel_hi:[1,0]
	v_pk_mul_f32 v[176:177], v[6:7], v[166:167] op_sel_hi:[1,0]
	v_pk_mul_f32 v[178:179], v[8:9], v[12:13]
	v_pk_mul_f32 v[180:181], v[10:11], v[14:15]
	v_pk_mul_f32 v[182:183], v[4:5], v[0:1]
	v_pk_mul_f32 v[184:185], v[6:7], v[2:3]
	v_exp_f32_e32 v170, v170
	v_exp_f32_e32 v171, v171
	v_exp_f32_e32 v172, v172
	v_exp_f32_e32 v173, v173
	v_exp_f32_e32 v174, v174
	v_exp_f32_e32 v175, v175
	v_exp_f32_e32 v176, v176
	v_exp_f32_e32 v177, v177
	s_nop 0
	v_pk_add_f32 v[170:171], v[170:171], v[164:165]
	v_pk_add_f32 v[172:173], v[172:173], v[164:165]
	v_pk_add_f32 v[174:175], v[174:175], v[164:165]
	v_pk_add_f32 v[176:177], v[176:177], v[164:165]
	v_rcp_f32_e32 v170, v170
	v_rcp_f32_e32 v171, v171
	v_rcp_f32_e32 v172, v172
	v_rcp_f32_e32 v173, v173
	v_rcp_f32_e32 v174, v174
	v_rcp_f32_e32 v175, v175
	v_rcp_f32_e32 v176, v176
	v_rcp_f32_e32 v177, v177
	s_nop 0
	v_pk_mul_f32 v[170:171], v[170:171], v[168:169] op_sel_hi:[1,0]
	v_pk_mul_f32 v[172:173], v[172:173], v[168:169] op_sel_hi:[1,0]
	v_pk_mul_f32 v[174:175], v[174:175], v[168:169] op_sel_hi:[1,0]
	v_pk_mul_f32 v[176:177], v[176:177], v[168:169] op_sel_hi:[1,0]
	v_pk_mul_f32 v[178:179], v[178:179], v[170:171]
	v_pk_mul_f32 v[180:181], v[180:181], v[172:173]
	v_pk_mul_f32 v[182:183], v[182:183], v[174:175]
	v_pk_mul_f32 v[184:185], v[184:185], v[176:177]
	v_cvt_pk_bf16_f32 v186, v178, v179
	v_cvt_pk_bf16_f32 v187, v180, v181
	v_cvt_pk_bf16_f32 v188, v182, v183
	v_cvt_pk_bf16_f32 v189, v184, v185
	s_and_b64 vcc, exec, s[2:3]
	s_mov_b64 s[2:3], -1
	global_store_dwordx4 v[160:161], v[186:189], off
	s_cbranch_vccnz .LBB0_1486
	s_andn2_b64 vcc, exec, s[16:17]
	s_cbranch_vccnz .LBB0_1485
	s_barrier
	s_branch .LBB0_1485
